# attention tile prefetch: removed two mid-sequence vmcnt(3) waits between the 8 K/V loads of a cache tile; rows l=0 staging: 15 dependent adaLN-partial loads issued together with counted waits
# speedup vs baseline: 1.0266x; 1.0085x over previous
.LBB0_226:
	global_load_dwordx4 v[44:47], v[44:45], off
	s_nop 0
	global_load_dwordx4 v[48:51], v[48:49], off
	global_load_dwordx4 v[52:55], v[52:53], off
	global_load_dwordx4 v[56:59], v[56:57], off

.LBB0_430:
	s_andn2_b64 vcc, exec, s[0:1]
	s_cbranch_vccnz .LBB0_432
	s_mul_i32 s0, s34, 0x1800
	s_ashr_i32 s1, s0, 31
	s_lshl_b64 s[0:1], s[0:1], 2
	v_readlane_b32 s34, v252, 18
	v_readlane_b32 s35, v252, 19
	s_add_u32 s0, s34, s0
	s_addc_u32 s1, s35, s1
	s_waitcnt vmcnt(1)
	v_lshl_add_u64 v[8:9], v[36:37], 2, s[0:1]
	global_load_dwordx4 v[4:7], v[58:59], off
	global_load_dwordx4 v[10:13], v[60:61], off
	global_load_dwordx4 v[14:17], v[8:9], off
	v_add_co_u32_e32 v104, vcc, 0x2000, v8
	s_nop 1
	v_addc_co_u32_e32 v105, vcc, 0, v9, vcc
	global_load_dwordx4 v[104:107], v[104:105], off
	v_add_co_u32_e32 v108, vcc, 0x78000, v8
	s_nop 1
	v_addc_co_u32_e32 v109, vcc, 0, v9, vcc
	global_load_dwordx4 v[108:111], v[108:109], off
	v_add_co_u32_e32 v112, vcc, 0x7a000, v8
	s_nop 1
	v_addc_co_u32_e32 v113, vcc, 0, v9, vcc
	global_load_dwordx4 v[112:115], v[112:113], off
	v_add_co_u32_e32 v116, vcc, 0xf0000, v8
	s_nop 1
	v_addc_co_u32_e32 v117, vcc, 0, v9, vcc
	global_load_dwordx4 v[116:119], v[116:117], off
	v_add_co_u32_e32 v120, vcc, 0xf2000, v8
	s_nop 1
	v_addc_co_u32_e32 v121, vcc, 0, v9, vcc
	global_load_dwordx4 v[120:123], v[120:121], off
	v_add_co_u32_e32 v124, vcc, 0x168000, v8
	s_nop 1
	v_addc_co_u32_e32 v125, vcc, 0, v9, vcc
	global_load_dwordx4 v[124:127], v[124:125], off
	v_add_co_u32_e32 v128, vcc, 0x16a000, v8
	s_nop 1
	v_addc_co_u32_e32 v129, vcc, 0, v9, vcc
	global_load_dwordx4 v[128:131], v[128:129], off
	v_add_co_u32_e32 v132, vcc, 0x1e0000, v8
	s_nop 1
	v_addc_co_u32_e32 v133, vcc, 0, v9, vcc
	global_load_dwordx4 v[132:135], v[132:133], off
	v_add_co_u32_e32 v136, vcc, 0x1e2000, v8
	s_nop 1
	v_addc_co_u32_e32 v137, vcc, 0, v9, vcc
	global_load_dwordx4 v[136:139], v[136:137], off
	v_add_co_u32_e32 v140, vcc, 0x258000, v8
	s_nop 1
	v_addc_co_u32_e32 v141, vcc, 0, v9, vcc
	global_load_dwordx4 v[140:143], v[140:141], off
	v_add_co_u32_e32 v148, vcc, 0x25a000, v8
	s_nop 1
	v_addc_co_u32_e32 v149, vcc, 0, v9, vcc
	global_load_dwordx4 v[148:151], v[148:149], off
	v_add_co_u32_e32 v152, vcc, 0x2d0000, v8
	s_nop 1
	v_addc_co_u32_e32 v153, vcc, 0, v9, vcc
	global_load_dwordx4 v[152:155], v[152:153], off
	v_add_co_u32_e32 v156, vcc, 0x2d2000, v8
	s_nop 1
	v_addc_co_u32_e32 v157, vcc, 0, v9, vcc
	global_load_dwordx4 v[156:159], v[156:157], off
	v_add_co_u32_e32 v160, vcc, 0x348000, v8
	s_nop 1
	v_addc_co_u32_e32 v161, vcc, 0, v9, vcc
	global_load_dwordx4 v[160:163], v[160:161], off
	v_add_co_u32_e32 v164, vcc, 0x34a000, v8
	s_nop 1
	v_addc_co_u32_e32 v165, vcc, 0, v9, vcc
	global_load_dwordx4 v[164:167], v[164:165], off
	s_movk_i32 s0, 0x2000
	s_waitcnt vmcnt(15)
	v_pk_add_f32 v[14:15], v[4:5], v[14:15]
	v_add_co_u32_e32 v4, vcc, s0, v8
	v_pk_add_f32 v[16:17], v[6:7], v[16:17]
	s_nop 0
	v_addc_co_u32_e32 v5, vcc, 0, v9, vcc
	s_waitcnt vmcnt(14)
	v_mov_b64_e32 v[4:5], v[104:105]
	v_mov_b64_e32 v[6:7], v[106:107]
	s_mov_b32 s0, 0x78000
	v_pk_add_f32 v[10:11], v[10:11], v[4:5]
	v_add_co_u32_e32 v4, vcc, s0, v8
	v_pk_add_f32 v[12:13], v[12:13], v[6:7]
	s_nop 0
	v_addc_co_u32_e32 v5, vcc, 0, v9, vcc
	s_waitcnt vmcnt(13)
	v_mov_b64_e32 v[4:5], v[108:109]
	v_mov_b64_e32 v[6:7], v[110:111]
	s_mov_b32 s0, 0x7a000
	v_pk_add_f32 v[14:15], v[14:15], v[4:5]
	v_add_co_u32_e32 v4, vcc, s0, v8
	v_pk_add_f32 v[16:17], v[16:17], v[6:7]
	s_nop 0
	v_addc_co_u32_e32 v5, vcc, 0, v9, vcc
	s_waitcnt vmcnt(12)
	v_mov_b64_e32 v[4:5], v[112:113]
	v_mov_b64_e32 v[6:7], v[114:115]
	s_mov_b32 s0, 0xf0000
	v_pk_add_f32 v[10:11], v[10:11], v[4:5]
	v_add_co_u32_e32 v4, vcc, s0, v8
	v_pk_add_f32 v[12:13], v[12:13], v[6:7]
	s_nop 0
	v_addc_co_u32_e32 v5, vcc, 0, v9, vcc
	s_waitcnt vmcnt(11)
	v_mov_b64_e32 v[4:5], v[116:117]
	v_mov_b64_e32 v[6:7], v[118:119]
	s_mov_b32 s0, 0xf2000
	v_pk_add_f32 v[14:15], v[14:15], v[4:5]
	v_add_co_u32_e32 v4, vcc, s0, v8
	v_pk_add_f32 v[16:17], v[16:17], v[6:7]
	s_nop 0
	v_addc_co_u32_e32 v5, vcc, 0, v9, vcc
	s_waitcnt vmcnt(10)
	v_mov_b64_e32 v[4:5], v[120:121]
	v_mov_b64_e32 v[6:7], v[122:123]
	s_mov_b32 s0, 0x168000
	v_pk_add_f32 v[10:11], v[10:11], v[4:5]
	v_add_co_u32_e32 v4, vcc, s0, v8
	v_pk_add_f32 v[12:13], v[12:13], v[6:7]
	s_nop 0
	v_addc_co_u32_e32 v5, vcc, 0, v9, vcc
	s_waitcnt vmcnt(9)
	v_mov_b64_e32 v[4:5], v[124:125]
	v_mov_b64_e32 v[6:7], v[126:127]
	s_mov_b32 s0, 0x16a000
	v_pk_add_f32 v[14:15], v[14:15], v[4:5]
	v_add_co_u32_e32 v4, vcc, s0, v8
	v_pk_add_f32 v[16:17], v[16:17], v[6:7]
	s_nop 0
	v_addc_co_u32_e32 v5, vcc, 0, v9, vcc
	s_waitcnt vmcnt(8)
	v_mov_b64_e32 v[4:5], v[128:129]
	v_mov_b64_e32 v[6:7], v[130:131]
	s_mov_b32 s0, 0x1e0000
	v_pk_add_f32 v[10:11], v[10:11], v[4:5]
	v_add_co_u32_e32 v4, vcc, s0, v8
	v_pk_add_f32 v[12:13], v[12:13], v[6:7]
	s_nop 0
	v_addc_co_u32_e32 v5, vcc, 0, v9, vcc
	s_waitcnt vmcnt(7)
	v_mov_b64_e32 v[4:5], v[132:133]
	v_mov_b64_e32 v[6:7], v[134:135]
	s_mov_b32 s0, 0x1e2000
	v_pk_add_f32 v[14:15], v[14:15], v[4:5]
	v_add_co_u32_e32 v4, vcc, s0, v8
	v_pk_add_f32 v[16:17], v[16:17], v[6:7]
	s_nop 0
	v_addc_co_u32_e32 v5, vcc, 0, v9, vcc
	s_waitcnt vmcnt(6)
	v_mov_b64_e32 v[4:5], v[136:137]
	v_mov_b64_e32 v[6:7], v[138:139]
	s_mov_b32 s0, 0x258000
	v_pk_add_f32 v[10:11], v[10:11], v[4:5]
	v_add_co_u32_e32 v4, vcc, s0, v8
	v_pk_add_f32 v[12:13], v[12:13], v[6:7]
	s_nop 0
	v_addc_co_u32_e32 v5, vcc, 0, v9, vcc
	s_waitcnt vmcnt(5)
	v_mov_b64_e32 v[4:5], v[140:141]
	v_mov_b64_e32 v[6:7], v[142:143]
	s_mov_b32 s0, 0x25a000
	v_pk_add_f32 v[14:15], v[14:15], v[4:5]
	v_add_co_u32_e32 v4, vcc, s0, v8
	v_pk_add_f32 v[16:17], v[16:17], v[6:7]
	s_nop 0
	v_addc_co_u32_e32 v5, vcc, 0, v9, vcc
	s_waitcnt vmcnt(4)
	v_mov_b64_e32 v[4:5], v[148:149]
	v_mov_b64_e32 v[6:7], v[150:151]
	s_mov_b32 s0, 0x2d0000
	v_pk_add_f32 v[10:11], v[10:11], v[4:5]
	v_add_co_u32_e32 v4, vcc, s0, v8
	v_pk_add_f32 v[12:13], v[12:13], v[6:7]
	s_nop 0
	v_addc_co_u32_e32 v5, vcc, 0, v9, vcc
	s_waitcnt vmcnt(3)
	v_mov_b64_e32 v[4:5], v[152:153]
	v_mov_b64_e32 v[6:7], v[154:155]
	s_mov_b32 s0, 0x2d2000
	v_pk_add_f32 v[14:15], v[14:15], v[4:5]
	v_add_co_u32_e32 v4, vcc, s0, v8
	v_pk_add_f32 v[16:17], v[16:17], v[6:7]
	s_nop 0
	v_addc_co_u32_e32 v5, vcc, 0, v9, vcc
	s_waitcnt vmcnt(2)
	v_mov_b64_e32 v[4:5], v[156:157]
	v_mov_b64_e32 v[6:7], v[158:159]
	s_mov_b32 s0, 0x348000
	v_pk_add_f32 v[18:19], v[10:11], v[4:5]
	v_add_co_u32_e32 v4, vcc, s0, v8
	v_pk_add_f32 v[12:13], v[12:13], v[6:7]
	s_nop 0
	v_addc_co_u32_e32 v5, vcc, 0, v9, vcc
	v_add_co_u32_e32 v8, vcc, 0x34a000, v8
	s_waitcnt vmcnt(1)
	v_mov_b64_e32 v[4:5], v[160:161]
	v_mov_b64_e32 v[6:7], v[162:163]
	s_nop 0
	v_addc_co_u32_e32 v9, vcc, 0, v9, vcc
	s_waitcnt vmcnt(0)
	v_mov_b64_e32 v[8:9], v[164:165]
	v_mov_b64_e32 v[10:11], v[166:167]
	v_pk_add_f32 v[6:7], v[16:17], v[6:7]
	v_pk_add_f32 v[4:5], v[14:15], v[4:5]
	v_pk_add_f32 v[10:11], v[12:13], v[10:11]
	v_pk_add_f32 v[8:9], v[18:19], v[8:9]
